# pre_phase x->residual copy loop: 4 grid-stride elements per pass with 4 loads in flight (was 1 load->wait->store per pass), on top of v50
# speedup vs baseline: 1.0052x; 1.0052x over previous
.LBB0_22:
	s_waitcnt lgkmcnt(0)
	s_mov_b64 s[100:101], exec
	v_mov_b32_e32 v162, v0
	v_lshl_add_u64 v[150:151], v[0:1], 4, s[8:9]
	v_lshl_add_u64 v[152:153], s[6:7], 0, v[2:3]
	v_lshl_add_u64 v[150:151], v[150:151], 0, s[16:17]
	v_cmp_gt_i32_e32 vcc, s11, v0
	v_lshl_add_u64 v[154:155], s[4:5], 0, v[2:3]
	s_nop 0
	v_cndmask_b32_e32 v153, v151, v153, vcc
	v_cndmask_b32_e32 v152, v150, v152, vcc
	global_load_dwordx4 v[130:133], v[152:153], off
	v_add_u32_e32 v0, s10, v0
	v_lshl_add_u64 v[2:3], v[2:3], 0, s[12:13]
	v_cmp_ge_i32_e32 vcc, s18, v0
	s_and_b64 exec, exec, vcc
	v_mov_b32_e32 v163, v0
	v_lshl_add_u64 v[150:151], v[0:1], 4, s[8:9]
	v_lshl_add_u64 v[152:153], s[6:7], 0, v[2:3]
	v_lshl_add_u64 v[150:151], v[150:151], 0, s[16:17]
	v_cmp_gt_i32_e32 vcc, s11, v0
	v_lshl_add_u64 v[156:157], s[4:5], 0, v[2:3]
	s_nop 0
	v_cndmask_b32_e32 v153, v151, v153, vcc
	v_cndmask_b32_e32 v152, v150, v152, vcc
	global_load_dwordx4 v[134:137], v[152:153], off
	v_add_u32_e32 v0, s10, v0
	v_lshl_add_u64 v[2:3], v[2:3], 0, s[12:13]
	v_cmp_ge_i32_e32 vcc, s18, v0
	s_and_b64 exec, exec, vcc
	v_mov_b32_e32 v164, v0
	v_lshl_add_u64 v[150:151], v[0:1], 4, s[8:9]
	v_lshl_add_u64 v[152:153], s[6:7], 0, v[2:3]
	v_lshl_add_u64 v[150:151], v[150:151], 0, s[16:17]
	v_cmp_gt_i32_e32 vcc, s11, v0
	v_lshl_add_u64 v[158:159], s[4:5], 0, v[2:3]
	s_nop 0
	v_cndmask_b32_e32 v153, v151, v153, vcc
	v_cndmask_b32_e32 v152, v150, v152, vcc
	global_load_dwordx4 v[138:141], v[152:153], off
	v_add_u32_e32 v0, s10, v0
	v_lshl_add_u64 v[2:3], v[2:3], 0, s[12:13]
	v_cmp_ge_i32_e32 vcc, s18, v0
	s_and_b64 exec, exec, vcc
	v_mov_b32_e32 v165, v0
	v_lshl_add_u64 v[150:151], v[0:1], 4, s[8:9]
	v_lshl_add_u64 v[152:153], s[6:7], 0, v[2:3]
	v_lshl_add_u64 v[150:151], v[150:151], 0, s[16:17]
	v_cmp_gt_i32_e32 vcc, s11, v0
	v_lshl_add_u64 v[160:161], s[4:5], 0, v[2:3]
	s_nop 0
	v_cndmask_b32_e32 v153, v151, v153, vcc
	v_cndmask_b32_e32 v152, v150, v152, vcc
	global_load_dwordx4 v[142:145], v[152:153], off
	v_add_u32_e32 v0, s10, v0
	v_lshl_add_u64 v[2:3], v[2:3], 0, s[12:13]
	s_mov_b64 exec, s[100:101]
	v_cmp_ge_i32_e32 vcc, s18, v162
	s_and_b64 exec, exec, vcc
	s_waitcnt vmcnt(3)
	global_store_dwordx4 v[154:155], v[130:133], off
	s_mov_b64 exec, s[100:101]
	v_cmp_ge_i32_e32 vcc, s18, v163
	s_and_b64 exec, exec, vcc
	s_waitcnt vmcnt(3)
	global_store_dwordx4 v[156:157], v[134:137], off
	s_mov_b64 exec, s[100:101]
	v_cmp_ge_i32_e32 vcc, s18, v164
	s_and_b64 exec, exec, vcc
	s_waitcnt vmcnt(3)
	global_store_dwordx4 v[158:159], v[138:141], off
	s_mov_b64 exec, s[100:101]
	v_cmp_ge_i32_e32 vcc, s18, v165
	s_and_b64 exec, exec, vcc
	s_waitcnt vmcnt(3)
	global_store_dwordx4 v[160:161], v[142:145], off
	s_mov_b64 exec, s[100:101]
	v_cmp_lt_i32_e32 vcc, s18, v0
	s_or_b64 s[14:15], vcc, s[14:15]
	s_andn2_b64 exec, exec, s[14:15]
	s_cbranch_execnz .LBB0_22
